# out-projection final-output stores write-through (sc1) instead of nt, so the grid barrier's L2 writeback has less to flush
# speedup vs baseline: 1.0050x; 1.0022x over previous
.LBB0_677:
	s_or_b64 exec, exec, s[8:9]
	s_waitcnt lgkmcnt(0)
	s_barrier
	global_load_dwordx4 v[12:15], v56, s[52:53]
	global_load_dwordx4 v[8:11], v56, s[52:53] offset:64
	global_load_dwordx4 v[4:7], v56, s[52:53] offset:512
	global_load_dwordx4 v[0:3], v56, s[52:53] offset:576
	v_lshl_add_u32 v133, v132, 2, 0
	v_add_u32_e32 v153, 0x1000, v133
	ds_read2_b32 v[158:159], v153 offset1:16
	ds_read2_b32 v[162:163], v153 offset0:32 offset1:48
	v_add_u32_e32 v132, s16, v132
	v_add_u32_e32 v154, 16, v132
	v_add_u32_e32 v156, 32, v132
	v_ashrrev_i32_e32 v155, 31, v154
	v_ashrrev_i32_e32 v133, 31, v132
	v_ashrrev_i32_e32 v157, 31, v156
	v_lshlrev_b64 v[154:155], 13, v[154:155]
	s_waitcnt lgkmcnt(1)
	v_pk_mul_f32 v[58:59], v[58:59], v[158:159] op_sel_hi:[1,0]
	v_mov_b32_e32 v57, 0
	v_lshlrev_b64 v[160:161], 13, v[132:133]
	v_lshlrev_b64 v[156:157], 13, v[156:157]
	v_lshl_add_u64 v[154:155], s[54:55], 0, v[154:155]
	s_waitcnt lgkmcnt(0)
	v_pk_mul_f32 v[174:175], v[90:91], v[162:163] op_sel_hi:[1,0]
	v_lshl_add_u64 v[160:161], s[54:55], 0, v[160:161]
	v_lshl_add_u64 v[156:157], s[54:55], 0, v[156:157]
	v_lshl_add_u64 v[164:165], v[154:155], 0, v[56:57]
	v_pk_mul_f32 v[128:129], v[128:129], v[158:159] op_sel_hi:[1,0]
	v_mov_b32_e32 v154, v159
	v_lshl_add_u64 v[160:161], v[160:161], 0, v[56:57]
	v_lshl_add_u64 v[166:167], v[156:157], 0, v[56:57]
	v_pk_mul_f32 v[124:125], v[124:125], v[158:159] op_sel_hi:[1,0]
	v_pk_mul_f32 v[126:127], v[126:127], v[158:159] op_sel_hi:[1,0]
	v_pk_mul_f32 v[120:121], v[120:121], v[158:159] op_sel_hi:[1,0]
	v_pk_mul_f32 v[122:123], v[122:123], v[158:159] op_sel_hi:[1,0]
	v_pk_mul_f32 v[116:117], v[116:117], v[158:159] op_sel_hi:[1,0]
	v_pk_mul_f32 v[118:119], v[118:119], v[158:159] op_sel_hi:[1,0]
	v_pk_mul_f32 v[156:157], v[96:97], v[162:163] op_sel_hi:[1,0]
	v_pk_mul_f32 v[158:159], v[98:99], v[162:163] op_sel_hi:[1,0]
	v_pk_mul_f32 v[168:169], v[92:93], v[162:163] op_sel_hi:[1,0]
	v_pk_mul_f32 v[170:171], v[94:95], v[162:163] op_sel_hi:[1,0]
	v_pk_mul_f32 v[172:173], v[88:89], v[162:163] op_sel_hi:[1,0]
	v_pk_mul_f32 v[112:113], v[112:113], v[154:155] op_sel_hi:[1,0]
	v_pk_mul_f32 v[114:115], v[114:115], v[154:155] op_sel_hi:[1,0]
	v_pk_mul_f32 v[108:109], v[108:109], v[154:155] op_sel_hi:[1,0]
	v_pk_mul_f32 v[110:111], v[110:111], v[154:155] op_sel_hi:[1,0]
	v_pk_mul_f32 v[182:183], v[104:105], v[154:155] op_sel_hi:[1,0]
	v_pk_mul_f32 v[184:185], v[106:107], v[154:155] op_sel_hi:[1,0]
	v_pk_mul_f32 v[186:187], v[100:101], v[154:155] op_sel_hi:[1,0]
	v_pk_mul_f32 v[154:155], v[102:103], v[154:155] op_sel_hi:[1,0]
	s_waitcnt vmcnt(3)
	v_pk_mul_f32 v[90:91], v[14:15], v[58:59]
	v_pk_mul_f32 v[58:59], v[84:85], v[162:163] op_sel_hi:[1,0]
	v_pk_mul_f32 v[84:85], v[86:87], v[162:163] op_sel_hi:[1,0]
	v_pk_mul_f32 v[88:89], v[12:13], v[128:129]
	s_waitcnt vmcnt(0)
	v_pk_mul_f32 v[86:87], v[2:3], v[84:85]
	v_pk_mul_f32 v[84:85], v[0:1], v[58:59]
	v_add_u32_e32 v58, 48, v132
	v_ashrrev_i32_e32 v59, 31, v58
	v_pk_mul_f32 v[94:95], v[10:11], v[126:127]
	v_pk_mul_f32 v[92:93], v[8:9], v[124:125]
	v_pk_mul_f32 v[98:99], v[6:7], v[122:123]
	v_pk_mul_f32 v[96:97], v[4:5], v[120:121]
	v_pk_mul_f32 v[102:103], v[2:3], v[118:119]
	v_pk_mul_f32 v[100:101], v[0:1], v[116:117]
	v_pk_mul_f32 v[106:107], v[14:15], v[114:115]
	v_pk_mul_f32 v[104:105], v[12:13], v[112:113]
	v_pk_mul_f32 v[110:111], v[10:11], v[110:111]
	v_pk_mul_f32 v[108:109], v[8:9], v[108:109]
	v_pk_mul_f32 v[114:115], v[6:7], v[184:185]
	v_pk_mul_f32 v[112:113], v[4:5], v[182:183]
	v_pk_mul_f32 v[118:119], v[2:3], v[154:155]
	v_pk_mul_f32 v[116:117], v[0:1], v[186:187]
	v_pk_mul_f32 v[122:123], v[14:15], v[158:159]
	v_pk_mul_f32 v[120:121], v[12:13], v[156:157]
	v_pk_mul_f32 v[126:127], v[10:11], v[170:171]
	v_pk_mul_f32 v[124:125], v[8:9], v[168:169]
	v_pk_mul_f32 v[156:157], v[6:7], v[174:175]
	v_pk_mul_f32 v[154:155], v[4:5], v[172:173]
	global_store_dwordx4 v[160:161], v[88:91], off sc1
	global_store_dwordx4 v[160:161], v[92:95], off offset:64 sc1
	global_store_dwordx4 v[160:161], v[96:99], off offset:512 sc1
	global_store_dwordx4 v[160:161], v[100:103], off offset:576 sc1
	global_store_dwordx4 v[164:165], v[104:107], off sc1
	global_store_dwordx4 v[164:165], v[108:111], off offset:64 sc1
	global_store_dwordx4 v[164:165], v[112:115], off offset:512 sc1
	global_store_dwordx4 v[164:165], v[116:119], off offset:576 sc1
	global_store_dwordx4 v[166:167], v[120:123], off sc1
	global_store_dwordx4 v[166:167], v[124:127], off offset:64 sc1
	global_store_dwordx4 v[166:167], v[154:157], off offset:512 sc1
	global_store_dwordx4 v[166:167], v[84:87], off offset:576 sc1
	v_lshlrev_b64 v[58:59], 13, v[58:59]
	v_lshl_add_u64 v[58:59], s[54:55], 0, v[58:59]
	v_mov_b32_e32 v84, v163
	v_pk_mul_f32 v[72:73], v[72:73], v[84:85] op_sel_hi:[1,0]
	v_pk_mul_f32 v[74:75], v[74:75], v[84:85] op_sel_hi:[1,0]
	v_lshl_add_u64 v[58:59], v[58:59], 0, v[56:57]
	v_pk_mul_f32 v[74:75], v[6:7], v[74:75]
	v_pk_mul_f32 v[72:73], v[4:5], v[72:73]
	v_pk_mul_f32 v[80:81], v[80:81], v[84:85] op_sel_hi:[1,0]
	v_pk_mul_f32 v[82:83], v[82:83], v[84:85] op_sel_hi:[1,0]
	v_pk_mul_f32 v[76:77], v[76:77], v[84:85] op_sel_hi:[1,0]
	v_pk_mul_f32 v[78:79], v[78:79], v[84:85] op_sel_hi:[1,0]
	global_store_dwordx4 v[58:59], v[72:75], off offset:512 sc1
	v_pk_mul_f32 v[68:69], v[68:69], v[84:85] op_sel_hi:[1,0]
	v_pk_mul_f32 v[70:71], v[70:71], v[84:85] op_sel_hi:[1,0]
	ds_read2_b32 v[72:73], v153 offset0:128 offset1:144
	v_pk_mul_f32 v[82:83], v[14:15], v[82:83]
	v_pk_mul_f32 v[80:81], v[12:13], v[80:81]
	v_pk_mul_f32 v[78:79], v[10:11], v[78:79]
	v_pk_mul_f32 v[76:77], v[8:9], v[76:77]
	v_pk_mul_f32 v[70:71], v[2:3], v[70:71]
	v_pk_mul_f32 v[68:69], v[0:1], v[68:69]
	global_store_dwordx4 v[58:59], v[80:83], off sc1
	global_store_dwordx4 v[58:59], v[76:79], off offset:64 sc1
	global_store_dwordx4 v[58:59], v[68:71], off offset:576 sc1
	v_add_u32_e32 v58, 0x80, v132
	v_ashrrev_i32_e32 v59, 31, v58
	v_lshlrev_b64 v[58:59], 13, v[58:59]
	v_lshl_add_u64 v[58:59], s[54:55], 0, v[58:59]
	s_waitcnt lgkmcnt(0)
	v_pk_mul_f32 v[48:49], v[48:49], v[72:73] op_sel_hi:[1,0]
	v_pk_mul_f32 v[50:51], v[50:51], v[72:73] op_sel_hi:[1,0]
	v_lshl_add_u64 v[68:69], v[58:59], 0, v[56:57]
	v_pk_mul_f32 v[50:51], v[2:3], v[50:51]
	v_pk_mul_f32 v[48:49], v[0:1], v[48:49]
	global_store_dwordx4 v[68:69], v[48:51], off offset:576 sc1
	v_pk_mul_f32 v[64:65], v[64:65], v[72:73] op_sel_hi:[1,0]
	v_pk_mul_f32 v[66:67], v[66:67], v[72:73] op_sel_hi:[1,0]
	v_add_u32_e32 v48, 0x90, v132
	v_ashrrev_i32_e32 v49, 31, v48
	v_lshlrev_b64 v[48:49], 13, v[48:49]
	v_mov_b32_e32 v50, v73
	v_lshl_add_u64 v[48:49], s[54:55], 0, v[48:49]
	v_pk_mul_f32 v[36:37], v[36:37], v[50:51] op_sel_hi:[1,0]
	v_pk_mul_f32 v[38:39], v[38:39], v[50:51] op_sel_hi:[1,0]
	v_lshl_add_u64 v[48:49], v[48:49], 0, v[56:57]
	v_pk_mul_f32 v[38:39], v[6:7], v[38:39]
	v_pk_mul_f32 v[36:37], v[4:5], v[36:37]
	global_store_dwordx4 v[48:49], v[36:39], off offset:512 sc1
	v_pk_mul_f32 v[32:33], v[32:33], v[50:51] op_sel_hi:[1,0]
	v_pk_mul_f32 v[34:35], v[34:35], v[50:51] op_sel_hi:[1,0]
	ds_read2_b32 v[36:37], v153 offset0:160 offset1:176
	v_pk_mul_f32 v[34:35], v[2:3], v[34:35]
	v_pk_mul_f32 v[32:33], v[0:1], v[32:33]
	global_store_dwordx4 v[48:49], v[32:35], off offset:576 sc1
	v_pk_mul_f32 v[44:45], v[44:45], v[50:51] op_sel_hi:[1,0]
	s_waitcnt lgkmcnt(0)
	v_pk_mul_f32 v[16:17], v[16:17], v[36:37] op_sel_hi:[1,0]
	v_add_u32_e32 v32, 0xa0, v132
	v_ashrrev_i32_e32 v33, 31, v32
	v_lshlrev_b64 v[32:33], 13, v[32:33]
	v_lshl_add_u64 v[32:33], s[54:55], 0, v[32:33]
	v_pk_mul_f32 v[18:19], v[18:19], v[36:37] op_sel_hi:[1,0]
	v_lshl_add_u64 v[32:33], v[32:33], 0, v[56:57]
	v_pk_mul_f32 v[18:19], v[2:3], v[18:19]
	v_pk_mul_f32 v[16:17], v[0:1], v[16:17]
	global_store_dwordx4 v[32:33], v[16:19], off offset:576 sc1
	v_pk_mul_f32 v[20:21], v[20:21], v[36:37] op_sel_hi:[1,0]
	v_pk_mul_f32 v[22:23], v[22:23], v[36:37] op_sel_hi:[1,0]
	v_add_u32_e32 v16, 0xb0, v132
	v_ashrrev_i32_e32 v17, 31, v16
	v_pk_mul_f32 v[22:23], v[6:7], v[22:23]
	v_pk_mul_f32 v[20:21], v[4:5], v[20:21]
	v_lshlrev_b64 v[16:17], 13, v[16:17]
	v_mov_b32_e32 v18, v37
	v_pk_mul_f32 v[46:47], v[46:47], v[50:51] op_sel_hi:[1,0]
	v_pk_mul_f32 v[28:29], v[28:29], v[36:37] op_sel_hi:[1,0]
	v_pk_mul_f32 v[30:31], v[30:31], v[36:37] op_sel_hi:[1,0]
	global_store_dwordx4 v[32:33], v[20:23], off offset:512 sc1
	v_lshl_add_u64 v[16:17], s[54:55], 0, v[16:17]
	v_pk_mul_f32 v[66:67], v[14:15], v[66:67]
	v_pk_mul_f32 v[20:21], v[140:141], v[18:19] op_sel_hi:[1,0]
	v_pk_mul_f32 v[22:23], v[134:135], v[18:19] op_sel_hi:[1,0]
	v_pk_mul_f32 v[64:65], v[12:13], v[64:65]
	v_pk_mul_f32 v[46:47], v[14:15], v[46:47]
	v_pk_mul_f32 v[44:45], v[12:13], v[44:45]
	v_pk_mul_f32 v[30:31], v[14:15], v[30:31]
	v_pk_mul_f32 v[28:29], v[12:13], v[28:29]
	v_pk_mul_f32 v[14:15], v[14:15], v[22:23]
	v_pk_mul_f32 v[12:13], v[12:13], v[20:21]
	v_lshl_add_u64 v[16:17], v[16:17], 0, v[56:57]
	v_pk_mul_f32 v[58:59], v[60:61], v[72:73] op_sel_hi:[1,0]
	v_pk_mul_f32 v[60:61], v[62:63], v[72:73] op_sel_hi:[1,0]
	v_pk_mul_f32 v[40:41], v[40:41], v[50:51] op_sel_hi:[1,0]
	v_pk_mul_f32 v[42:43], v[42:43], v[50:51] op_sel_hi:[1,0]
	v_pk_mul_f32 v[24:25], v[24:25], v[36:37] op_sel_hi:[1,0]
	v_pk_mul_f32 v[26:27], v[26:27], v[36:37] op_sel_hi:[1,0]
	global_store_dwordx4 v[16:17], v[12:15], off sc1
	v_pk_mul_f32 v[60:61], v[10:11], v[60:61]
	v_pk_mul_f32 v[58:59], v[8:9], v[58:59]
	v_pk_mul_f32 v[12:13], v[138:139], v[18:19] op_sel_hi:[1,0]
	v_pk_mul_f32 v[14:15], v[130:131], v[18:19] op_sel_hi:[1,0]
	v_pk_mul_f32 v[42:43], v[10:11], v[42:43]
	v_pk_mul_f32 v[40:41], v[8:9], v[40:41]
	v_pk_mul_f32 v[26:27], v[10:11], v[26:27]
	v_pk_mul_f32 v[24:25], v[8:9], v[24:25]
	v_pk_mul_f32 v[10:11], v[10:11], v[14:15]
	v_pk_mul_f32 v[8:9], v[8:9], v[12:13]
	v_pk_mul_f32 v[52:53], v[52:53], v[72:73] op_sel_hi:[1,0]
	v_pk_mul_f32 v[54:55], v[54:55], v[72:73] op_sel_hi:[1,0]
	global_store_dwordx4 v[16:17], v[8:11], off offset:64 sc1
	v_pk_mul_f32 v[54:55], v[6:7], v[54:55]
	v_pk_mul_f32 v[52:53], v[4:5], v[52:53]
	v_pk_mul_f32 v[8:9], v[144:145], v[18:19] op_sel_hi:[1,0]
	v_pk_mul_f32 v[10:11], v[136:137], v[18:19] op_sel_hi:[1,0]
	v_pk_mul_f32 v[4:5], v[4:5], v[8:9]
	v_pk_mul_f32 v[6:7], v[6:7], v[10:11]
	global_store_dwordx4 v[16:17], v[4:7], off offset:512 sc1
	global_store_dwordx4 v[68:69], v[64:67], off sc1
	global_store_dwordx4 v[68:69], v[58:61], off offset:64 sc1
	v_pk_mul_f32 v[4:5], v[146:147], v[18:19] op_sel_hi:[1,0]
	v_pk_mul_f32 v[6:7], v[142:143], v[18:19] op_sel_hi:[1,0]
	v_pk_mul_f32 v[0:1], v[0:1], v[4:5]
	v_pk_mul_f32 v[2:3], v[2:3], v[6:7]
	global_store_dwordx4 v[68:69], v[52:55], off offset:512 sc1
	global_store_dwordx4 v[48:49], v[44:47], off sc1
	global_store_dwordx4 v[48:49], v[40:43], off offset:64 sc1
	global_store_dwordx4 v[32:33], v[28:31], off sc1
	global_store_dwordx4 v[32:33], v[24:27], off offset:64 sc1
	global_store_dwordx4 v[16:17], v[0:3], off offset:576 sc1
	s_waitcnt vmcnt(0)
	s_barrier
	s_and_saveexec_b64 s[4:5], s[98:99]
	s_cbranch_execz .LBB0_729
	s_add_i32 s3, 0, 0x21000
	v_mov_b32_e32 v0, s3
	s_waitcnt vmcnt(0) expcnt(0) lgkmcnt(0)
	ds_read_b32 v2, v0
	s_add_i32 s3, 0, 0x21004
	v_mov_b32_e32 v0, s3
	ds_read_b32 v0, v0
	s_waitcnt lgkmcnt(1)
	v_cmp_ne_u32_e32 vcc, 0, v2
	s_cbranch_vccnz .LBB0_693
	s_mul_i32 s3, s17, s92
	s_lshl_b32 s3, s3, 8
	s_add_u32 s6, s56, 0x13daa200
	s_addc_u32 s7, s57, 0
	s_add_u32 s8, s56, 0x13daa400
	s_addc_u32 s9, s57, 0
	s_add_u32 s10, s56, 0x13daa500
	s_addc_u32 s11, s57, 0
	s_add_u32 s12, s56, 0x13daa600
	s_addc_u32 s13, s57, 0
	s_add_u32 s16, s56, 0x13daa700
	s_addc_u32 s17, s57, 0
	s_add_u32 s18, s56, 0x13daa800
	s_addc_u32 s19, s57, 0
	s_add_u32 s20, s56, 0x13daa900
	s_addc_u32 s21, s57, 0
	s_add_u32 s22, s56, 0x13daaa00
	s_addc_u32 s23, s57, 0
	s_add_u32 s24, s56, 0x13daab00
	s_addc_u32 s25, s57, 0
	s_add_u32 s26, s56, 0x13daac00
	s_addc_u32 s27, s57, 0
	s_add_u32 s28, s56, 0x13daad00
	s_addc_u32 s29, s57, 0
	s_add_u32 s30, s56, 0x13daae00
	s_addc_u32 s31, s57, 0
	s_add_u32 s34, s56, 0x13daaf00
	s_addc_u32 s35, s57, 0
	s_add_u32 s36, s56, 0x13dab000
	s_addc_u32 s37, s57, 0
	s_add_u32 s38, s56, 0x13dab100
	s_addc_u32 s39, s57, 0
	s_add_u32 s40, s56, 0x13dab200
	s_addc_u32 s41, s57, 0
	s_add_u32 s42, s56, 0x13dab300
	s_addc_u32 s43, s57, 0
	s_mov_b32 s33, 1
	v_mov_b32_e32 v16, 0
	s_branch .LBB0_681
